# v13 plus: indexer relu emitted as one v_max (canonicalizing v_max x,x dropped; denorm mode 3 keeps it a no-op), MFMA-VALU distances re-padded
# speedup vs baseline: 1.0146x; 1.0146x over previous
.LBB0_797:
	ds_read_b128 v[2:5], v139
	ds_read_b128 v[18:21], v139 offset:32
	ds_read_b128 v[22:25], v139 offset:64
	ds_read_b128 v[26:29], v139 offset:96
	ds_read_b128 v[34:37], v139 offset:4608
	ds_read_b128 v[30:33], v139 offset:4640
	ds_read_b128 v[174:177], v139 offset:4672
	ds_read_b128 v[184:187], v139 offset:4704
	ds_read_b128 v[188:191], v139 offset:9216
	ds_read_b128 v[192:195], v139 offset:9248
	ds_read_b128 v[196:199], v139 offset:9280
	ds_read_b128 v[200:203], v139 offset:9312
	s_mov_b32 s8, s7
	s_add_i32 s7, s7, 4
	s_add_i32 s8, s8, 7
	s_waitcnt lgkmcnt(11)
	v_mfma_f32_32x32x16_bf16 v[2:17], v[58:61], v[2:5], 0
	s_cmp_ge_i32 s8, s6
	s_waitcnt lgkmcnt(10)
	v_mfma_f32_32x32x16_bf16 v[2:17], v[54:57], v[18:21], v[2:17]
	s_waitcnt lgkmcnt(9)
	v_mfma_f32_32x32x16_bf16 v[2:17], v[50:53], v[22:25], v[2:17]
	s_waitcnt lgkmcnt(8)
	v_mfma_f32_32x32x16_bf16 v[2:17], v[62:65], v[26:29], v[2:17]
	s_waitcnt lgkmcnt(7)
	v_mfma_f32_32x32x16_bf16 v[34:49], v[58:61], v[34:37], 0
	s_nop 7
	s_nop 1
	v_max_f32_e32 v2, 0, v2
	v_fma_f32 v140, v120, v2, 0
	v_max_f32_e32 v2, 0, v10
	v_fma_f32 v141, v121, v2, 0
	s_waitcnt lgkmcnt(6)
	v_mfma_f32_32x32x16_bf16 v[34:49], v[54:57], v[30:33], v[34:49]
	v_max_f32_e32 v2, 0, v3
	v_fmac_f32_e32 v140, v122, v2
	v_max_f32_e32 v2, 0, v11
	v_fmac_f32_e32 v141, v123, v2
	s_waitcnt lgkmcnt(5)
	v_mfma_f32_32x32x16_bf16 v[34:49], v[50:53], v[174:177], v[34:49]
	v_max_f32_e32 v2, 0, v4
	v_fmac_f32_e32 v140, v124, v2
	v_max_f32_e32 v2, 0, v12
	v_fmac_f32_e32 v141, v125, v2
	s_waitcnt lgkmcnt(4)
	v_mfma_f32_32x32x16_bf16 v[34:49], v[62:65], v[184:187], v[34:49]
	v_max_f32_e32 v2, 0, v5
	v_fmac_f32_e32 v140, v126, v2
	v_max_f32_e32 v2, 0, v13
	v_fmac_f32_e32 v141, v127, v2
	s_waitcnt lgkmcnt(3)
	v_mfma_f32_32x32x16_bf16 v[18:33], v[58:61], v[188:191], 0
	v_max_f32_e32 v2, 0, v6
	v_fmac_f32_e32 v140, v128, v2
	v_max_f32_e32 v2, 0, v14
	v_fmac_f32_e32 v141, v129, v2
	s_waitcnt lgkmcnt(2)
	v_mfma_f32_32x32x16_bf16 v[18:33], v[54:57], v[192:195], v[18:33]
	v_max_f32_e32 v2, 0, v7
	v_fmac_f32_e32 v140, v130, v2
	v_max_f32_e32 v2, 0, v15
	v_fmac_f32_e32 v141, v131, v2
	s_waitcnt lgkmcnt(1)
	v_mfma_f32_32x32x16_bf16 v[18:33], v[50:53], v[196:199], v[18:33]
	v_max_f32_e32 v2, 0, v8
	v_fmac_f32_e32 v140, v132, v2
	v_max_f32_e32 v2, 0, v16
	v_fmac_f32_e32 v141, v133, v2
	v_max_f32_e32 v2, 0, v9
	s_waitcnt lgkmcnt(0)
	v_mfma_f32_32x32x16_bf16 v[18:33], v[62:65], v[200:203], v[18:33]
	ds_read_b128 v[110:113], v139 offset:13824
	ds_read_b128 v[106:109], v139 offset:13856
	ds_read_b128 v[102:105], v139 offset:13888
	ds_read_b128 v[98:101], v139 offset:13920
	v_fmac_f32_e32 v140, v134, v2
	v_max_f32_e32 v2, 0, v17
	v_fmac_f32_e32 v141, v135, v2
	v_max_f32_e32 v34, 0, v34
	s_waitcnt lgkmcnt(3)
	v_mfma_f32_32x32x16_bf16 v[2:17], v[58:61], v[110:113], 0
	s_nop 1
	v_max_f32_e32 v18, 0, v18
	v_add_u32_e32 v139, 0x4800, v139
	s_waitcnt lgkmcnt(2)
	v_mfma_f32_32x32x16_bf16 v[2:17], v[54:57], v[106:109], v[2:17]
	v_add_f32_e32 v106, 0, v141
	s_waitcnt lgkmcnt(1)
	v_mfma_f32_32x32x16_bf16 v[2:17], v[50:53], v[102:105], v[2:17]
	v_add_f32_e32 v102, 0, v140
	v_ashrrev_i32_e32 v103, 31, v102
	v_lshlrev_b64 v[104:105], 2, v[148:149]
	v_bitop3_b32 v107, v103, v102, s75 bitop3:0x36
	v_lshl_add_u64 v[102:103], v[116:117], 0, v[104:105]
	global_store_dword v[102:103], v107, off nt
	v_ashrrev_i32_e32 v107, 31, v106
	v_bitop3_b32 v106, v107, v106, s75 bitop3:0x36
	v_lshl_add_u64 v[104:105], v[118:119], 0, v[104:105]
	global_store_dword v[104:105], v106, off nt
	v_fma_f32 v104, v120, v34, 0
	v_max_f32_e32 v34, 0, v42
	v_fma_f32 v42, v121, v34, 0
	v_max_f32_e32 v34, 0, v35
	v_fmac_f32_e32 v104, v122, v34
	v_max_f32_e32 v34, 0, v43
	v_fmac_f32_e32 v42, v123, v34
	v_max_f32_e32 v34, 0, v36
	v_fmac_f32_e32 v104, v124, v34
	v_max_f32_e32 v34, 0, v44
	v_fmac_f32_e32 v42, v125, v34
	v_max_f32_e32 v34, 0, v37
	v_fmac_f32_e32 v104, v126, v34
	v_max_f32_e32 v34, 0, v45
	v_fmac_f32_e32 v42, v127, v34
	v_max_f32_e32 v34, 0, v38
	v_fmac_f32_e32 v104, v128, v34
	v_max_f32_e32 v34, 0, v46
	v_fmac_f32_e32 v42, v129, v34
	v_max_f32_e32 v34, 0, v39
	v_fmac_f32_e32 v104, v130, v34
	v_max_f32_e32 v34, 0, v47
	v_fmac_f32_e32 v42, v131, v34
	v_max_f32_e32 v34, 0, v40
	v_fmac_f32_e32 v104, v132, v34
	v_max_f32_e32 v34, 0, v48
	v_fmac_f32_e32 v42, v133, v34
	v_max_f32_e32 v34, 0, v41
	v_fmac_f32_e32 v104, v134, v34
	v_max_f32_e32 v34, 0, v49
	v_add_f32_e32 v35, 0, v104
	v_fmac_f32_e32 v42, v135, v34
	v_ashrrev_i32_e32 v37, 31, v35
	v_add_f32_e32 v36, 0, v42
	v_bitop3_b32 v37, v37, v35, s75 bitop3:0x36
	v_add_u32_e32 v34, 32, v148
	v_mov_b32_e32 v35, v149
	global_store_dword v[102:103], v37, off offset:128 nt
	v_ashrrev_i32_e32 v37, 31, v36
	v_bitop3_b32 v36, v37, v36, s75 bitop3:0x36
	v_lshl_add_u64 v[34:35], v[34:35], 2, v[118:119]
	global_store_dword v[34:35], v36, off nt
	v_fma_f32 v34, v120, v18, 0
	v_max_f32_e32 v18, 0, v26
	v_fma_f32 v26, v121, v18, 0
	v_max_f32_e32 v18, 0, v19
	v_fmac_f32_e32 v34, v122, v18
	v_max_f32_e32 v18, 0, v27
	v_fmac_f32_e32 v26, v123, v18
	v_max_f32_e32 v18, 0, v20
	v_fmac_f32_e32 v34, v124, v18
	v_max_f32_e32 v18, 0, v28
	v_fmac_f32_e32 v26, v125, v18
	v_max_f32_e32 v18, 0, v21
	v_fmac_f32_e32 v34, v126, v18
	v_max_f32_e32 v18, 0, v29
	v_fmac_f32_e32 v26, v127, v18
	v_max_f32_e32 v18, 0, v22
	v_fmac_f32_e32 v34, v128, v18
	v_max_f32_e32 v18, 0, v30
	v_fmac_f32_e32 v26, v129, v18
	v_max_f32_e32 v18, 0, v23
	v_fmac_f32_e32 v34, v130, v18
	v_max_f32_e32 v18, 0, v31
	v_fmac_f32_e32 v26, v131, v18
	v_max_f32_e32 v18, 0, v24
	v_fmac_f32_e32 v34, v132, v18
	s_waitcnt lgkmcnt(0)
	v_mfma_f32_32x32x16_bf16 v[2:17], v[62:65], v[98:101], v[2:17]
	v_max_f32_e32 v18, 0, v32
	v_fmac_f32_e32 v26, v133, v18
	v_max_f32_e32 v18, 0, v25
	v_fmac_f32_e32 v34, v134, v18
	v_max_f32_e32 v18, 0, v33
	v_add_f32_e32 v19, 0, v34
	v_fmac_f32_e32 v26, v135, v18
	v_ashrrev_i32_e32 v21, 31, v19
	v_add_f32_e32 v20, 0, v26
	v_bitop3_b32 v21, v21, v19, s75 bitop3:0x36
	v_add_u32_e32 v18, 64, v148
	v_mov_b32_e32 v19, v149
	global_store_dword v[102:103], v21, off offset:256 nt
	v_ashrrev_i32_e32 v21, 31, v20
	v_bitop3_b32 v20, v21, v20, s75 bitop3:0x36
	v_lshl_add_u64 v[18:19], v[18:19], 2, v[118:119]
	v_max_f32_e32 v2, 0, v2
	global_store_dword v[18:19], v20, off nt
	v_fma_f32 v18, v120, v2, 0
	v_max_f32_e32 v2, 0, v10
	v_fma_f32 v10, v121, v2, 0
	v_max_f32_e32 v2, 0, v3
	v_fmac_f32_e32 v18, v122, v2
	v_max_f32_e32 v2, 0, v11
	v_fmac_f32_e32 v10, v123, v2
	v_max_f32_e32 v2, 0, v4
	v_fmac_f32_e32 v18, v124, v2
	v_max_f32_e32 v2, 0, v12
	v_fmac_f32_e32 v10, v125, v2
	v_max_f32_e32 v2, 0, v5
	v_fmac_f32_e32 v18, v126, v2
	v_max_f32_e32 v2, 0, v13
	v_fmac_f32_e32 v10, v127, v2
	v_max_f32_e32 v2, 0, v6
	v_fmac_f32_e32 v18, v128, v2
	v_max_f32_e32 v2, 0, v14
	v_fmac_f32_e32 v10, v129, v2
	v_max_f32_e32 v2, 0, v7
	v_fmac_f32_e32 v18, v130, v2
	v_max_f32_e32 v2, 0, v15
	v_fmac_f32_e32 v10, v131, v2
	v_max_f32_e32 v2, 0, v8
	v_fmac_f32_e32 v18, v132, v2
	v_max_f32_e32 v2, 0, v16
	v_fmac_f32_e32 v10, v133, v2
	v_max_f32_e32 v2, 0, v9
	v_fmac_f32_e32 v18, v134, v2
	v_max_f32_e32 v2, 0, v17
	v_add_f32_e32 v3, 0, v18
	v_fmac_f32_e32 v10, v135, v2
	v_ashrrev_i32_e32 v5, 31, v3
	v_add_f32_e32 v4, 0, v10
	v_bitop3_b32 v5, v5, v3, s75 bitop3:0x36
	v_add_u32_e32 v2, 0x60, v148
	v_mov_b32_e32 v3, v149
	global_store_dword v[102:103], v5, off offset:384 nt
	v_ashrrev_i32_e32 v5, 31, v4
	v_bitop3_b32 v4, v5, v4, s75 bitop3:0x36
	v_lshl_add_u64 v[2:3], v[2:3], 2, v[118:119]
	v_add_u32_e32 v148, 0x80, v148
	global_store_dword v[2:3], v4, off nt
	s_cbranch_scc0 .LBB0_797

.LBB0_800:
	ds_read_b128 v[2:5], v22
	ds_read_b128 v[18:21], v22 offset:32
	s_add_i32 s7, s7, 1
	s_cmp_ge_i32 s7, s6
	s_waitcnt lgkmcnt(1)
	v_mfma_f32_32x32x16_bf16 v[2:17], v[58:61], v[2:5], 0
	s_waitcnt lgkmcnt(0)
	v_mfma_f32_32x32x16_bf16 v[2:17], v[54:57], v[18:21], v[2:17]
	ds_read_b128 v[24:27], v22 offset:64
	ds_read_b128 v[18:21], v22 offset:96
	v_add_u32_e32 v22, 0x1200, v22
	s_waitcnt lgkmcnt(1)
	v_mfma_f32_32x32x16_bf16 v[2:17], v[50:53], v[24:27], v[2:17]
	v_lshlrev_b64 v[24:25], 2, v[148:149]
	v_add_u32_e32 v148, 32, v148
	v_lshl_add_u64 v[26:27], v[116:117], 0, v[24:25]
	v_lshl_add_u64 v[24:25], v[118:119], 0, v[24:25]
	s_waitcnt lgkmcnt(0)
	v_mfma_f32_32x32x16_bf16 v[2:17], v[62:65], v[18:21], v[2:17]
	s_nop 11
	v_max_f32_e32 v2, 0, v2
	v_max_f32_e32 v10, 0, v10
	v_max_f32_e32 v3, 0, v3
	v_fma_f32 v2, v120, v2, 0
	v_max_f32_e32 v11, 0, v11
	v_max_f32_e32 v4, 0, v4
	v_fma_f32 v10, v121, v10, 0
	v_fmac_f32_e32 v2, v122, v3
	v_max_f32_e32 v12, 0, v12
	v_max_f32_e32 v5, 0, v5
	v_fmac_f32_e32 v10, v123, v11
	v_fmac_f32_e32 v2, v124, v4
	v_max_f32_e32 v13, 0, v13
	v_max_f32_e32 v6, 0, v6
	v_fmac_f32_e32 v10, v125, v12
	v_fmac_f32_e32 v2, v126, v5
	v_max_f32_e32 v14, 0, v14
	v_max_f32_e32 v7, 0, v7
	v_fmac_f32_e32 v10, v127, v13
	v_fmac_f32_e32 v2, v128, v6
	v_max_f32_e32 v15, 0, v15
	v_max_f32_e32 v8, 0, v8
	v_fmac_f32_e32 v10, v129, v14
	v_fmac_f32_e32 v2, v130, v7
	v_max_f32_e32 v16, 0, v16
	v_max_f32_e32 v9, 0, v9
	v_fmac_f32_e32 v10, v131, v15
	v_fmac_f32_e32 v2, v132, v8
	v_max_f32_e32 v17, 0, v17
	v_fmac_f32_e32 v10, v133, v16
	v_fmac_f32_e32 v2, v134, v9
	v_fmac_f32_e32 v10, v135, v17
	v_add_f32_e32 v2, 0, v2
	v_add_f32_e32 v3, 0, v10
	v_ashrrev_i32_e32 v4, 31, v2
	v_ashrrev_i32_e32 v5, 31, v3
	v_bitop3_b32 v2, v4, v2, s75 bitop3:0x36
	v_bitop3_b32 v3, v5, v3, s75 bitop3:0x36
	global_store_dword v[26:27], v2, off nt
	global_store_dword v[24:25], v3, off nt
	s_cbranch_scc0 .LBB0_800
	s_branch .LBB0_792

.LBB0_3056:
	ds_read_b128 v[2:5], v161
	ds_read_b128 v[114:117], v161 offset:32
	ds_read_b128 v[18:21], v161 offset:4608
	ds_read_b128 v[118:121], v161 offset:4640
	ds_read_b128 v[34:37], v161 offset:9216
	ds_read_b128 v[122:125], v161 offset:9248
	ds_read_b128 v[50:53], v161 offset:13824
	ds_read_b128 v[132:135], v161 offset:13856
	s_waitcnt lgkmcnt(7)
	v_mfma_f32_32x32x16_bf16 v[2:17], v[74:77], v[2:5], 0
	s_mov_b32 s10, s9
	s_add_i32 s9, s9, 4
	s_add_i32 s10, s10, 7
	v_add_u32_e32 v136, 64, v148
	v_mov_b32_e32 v137, v149
	s_cmp_ge_i32 s10, s8
	s_waitcnt lgkmcnt(5)
	v_mfma_f32_32x32x16_bf16 v[18:33], v[74:77], v[18:21], 0
	s_waitcnt lgkmcnt(1)
	v_mfma_f32_32x32x16_bf16 v[50:65], v[74:77], v[50:53], 0
	v_mfma_f32_32x32x16_bf16 v[34:49], v[74:77], v[34:37], 0
	v_mfma_f32_32x32x16_bf16 v[2:17], v[70:73], v[114:117], v[2:17]
	v_mfma_f32_32x32x16_bf16 v[18:33], v[70:73], v[118:121], v[18:33]
	s_waitcnt lgkmcnt(0)
	v_mfma_f32_32x32x16_bf16 v[50:65], v[70:73], v[132:135], v[50:65]
	ds_read_b128 v[114:117], v161 offset:64
	ds_read_b128 v[132:135], v161 offset:96
	v_mfma_f32_32x32x16_bf16 v[34:49], v[70:73], v[122:125], v[34:49]
	s_waitcnt lgkmcnt(1)
	v_mfma_f32_32x32x16_bf16 v[2:17], v[66:69], v[114:117], v[2:17]
	ds_read_b128 v[114:117], v161 offset:4672
	ds_read_b128 v[122:125], v161 offset:4704
	s_waitcnt lgkmcnt(1)
	v_mfma_f32_32x32x16_bf16 v[18:33], v[66:69], v[114:117], v[18:33]
	ds_read_b128 v[114:117], v161 offset:9280
	ds_read_b128 v[118:121], v161 offset:9312
	s_waitcnt lgkmcnt(1)
	v_mfma_f32_32x32x16_bf16 v[34:49], v[66:69], v[114:117], v[34:49]
	ds_read_b128 v[162:165], v161 offset:13888
	ds_read_b128 v[114:117], v161 offset:13920
	v_add_u32_e32 v161, 0x4800, v161
	s_waitcnt lgkmcnt(1)
	v_mfma_f32_32x32x16_bf16 v[50:65], v[66:69], v[162:165], v[50:65]
	v_mfma_f32_32x32x16_bf16 v[2:17], v[78:81], v[132:135], v[2:17]
	v_lshlrev_b64 v[132:133], 2, v[148:149]
	v_add_u32_e32 v134, 32, v148
	v_mov_b32_e32 v135, v149
	v_mfma_f32_32x32x16_bf16 v[18:33], v[78:81], v[122:125], v[18:33]
	s_nop 7
	v_max_f32_e32 v2, 0, v2
	v_max_f32_e32 v10, 0, v10
	v_mfma_f32_32x32x16_bf16 v[34:49], v[78:81], v[118:121], v[34:49]
	v_max_f32_e32 v3, 0, v3
	v_max_f32_e32 v18, 0, v18
	v_max_f32_e32 v26, 0, v26
	s_waitcnt lgkmcnt(0)
	v_mfma_f32_32x32x16_bf16 v[50:65], v[78:81], v[114:117], v[50:65]
	s_nop 2
	s_nop 3
	v_max_f32_e32 v34, 0, v34
	v_max_f32_e32 v42, 0, v42
	v_fma_f32 v2, v138, v2, 0
	s_nop 1
	v_max_f32_e32 v50, 0, v50
	v_max_f32_e32 v58, 0, v58
	v_max_f32_e32 v11, 0, v11
	v_max_f32_e32 v4, 0, v4
	v_max_f32_e32 v19, 0, v19
	v_max_f32_e32 v27, 0, v27
	v_max_f32_e32 v35, 0, v35
	v_max_f32_e32 v43, 0, v43
	v_max_f32_e32 v51, 0, v51
	v_max_f32_e32 v59, 0, v59
	v_fma_f32 v10, v139, v10, 0
	v_fma_f32 v18, v138, v18, 0
	v_fma_f32 v26, v139, v26, 0
	v_fma_f32 v34, v138, v34, 0
	v_fma_f32 v42, v139, v42, 0
	v_fma_f32 v50, v138, v50, 0
	v_fma_f32 v58, v139, v58, 0
	v_fmac_f32_e32 v2, v140, v3
	v_max_f32_e32 v12, 0, v12
	v_max_f32_e32 v5, 0, v5
	v_max_f32_e32 v20, 0, v20
	v_max_f32_e32 v28, 0, v28
	v_max_f32_e32 v36, 0, v36
	v_max_f32_e32 v44, 0, v44
	v_max_f32_e32 v52, 0, v52
	v_max_f32_e32 v60, 0, v60
	v_fmac_f32_e32 v10, v141, v11
	v_fmac_f32_e32 v18, v140, v19
	v_fmac_f32_e32 v26, v141, v27
	v_fmac_f32_e32 v34, v140, v35
	v_fmac_f32_e32 v42, v141, v43
	v_fmac_f32_e32 v50, v140, v51
	v_fmac_f32_e32 v58, v141, v59
	v_fmac_f32_e32 v2, v142, v4
	v_max_f32_e32 v13, 0, v13
	v_max_f32_e32 v6, 0, v6
	v_max_f32_e32 v21, 0, v21
	v_max_f32_e32 v29, 0, v29
	v_max_f32_e32 v37, 0, v37
	v_max_f32_e32 v45, 0, v45
	v_max_f32_e32 v53, 0, v53
	v_max_f32_e32 v61, 0, v61
	v_fmac_f32_e32 v10, v143, v12
	v_fmac_f32_e32 v18, v142, v20
	v_fmac_f32_e32 v26, v143, v28
	v_fmac_f32_e32 v34, v142, v36
	v_fmac_f32_e32 v42, v143, v44
	v_fmac_f32_e32 v50, v142, v52
	v_fmac_f32_e32 v58, v143, v60
	v_fmac_f32_e32 v2, v144, v5
	v_max_f32_e32 v14, 0, v14
	v_max_f32_e32 v7, 0, v7
	v_max_f32_e32 v22, 0, v22
	v_max_f32_e32 v30, 0, v30
	v_max_f32_e32 v38, 0, v38
	v_max_f32_e32 v46, 0, v46
	v_max_f32_e32 v54, 0, v54
	v_max_f32_e32 v62, 0, v62
	v_fmac_f32_e32 v10, v145, v13
	v_fmac_f32_e32 v18, v144, v21
	v_fmac_f32_e32 v26, v145, v29
	v_fmac_f32_e32 v34, v144, v37
	v_fmac_f32_e32 v42, v145, v45
	v_fmac_f32_e32 v50, v144, v53
	v_fmac_f32_e32 v58, v145, v61
	v_fmac_f32_e32 v2, v150, v6
	v_max_f32_e32 v15, 0, v15
	v_max_f32_e32 v8, 0, v8
	v_max_f32_e32 v23, 0, v23
	v_max_f32_e32 v31, 0, v31
	v_max_f32_e32 v39, 0, v39
	v_max_f32_e32 v47, 0, v47
	v_max_f32_e32 v55, 0, v55
	v_max_f32_e32 v63, 0, v63
	v_fmac_f32_e32 v10, v151, v14
	v_fmac_f32_e32 v18, v150, v22
	v_fmac_f32_e32 v26, v151, v30
	v_fmac_f32_e32 v34, v150, v38
	v_fmac_f32_e32 v42, v151, v46
	v_fmac_f32_e32 v50, v150, v54
	v_fmac_f32_e32 v58, v151, v62
	v_fmac_f32_e32 v2, v152, v7
	v_max_f32_e32 v16, 0, v16
	v_max_f32_e32 v9, 0, v9
	v_max_f32_e32 v24, 0, v24
	v_max_f32_e32 v32, 0, v32
	v_max_f32_e32 v40, 0, v40
	v_max_f32_e32 v48, 0, v48
	v_max_f32_e32 v56, 0, v56
	v_max_f32_e32 v64, 0, v64
	v_fmac_f32_e32 v10, v153, v15
	v_fmac_f32_e32 v18, v152, v23
	v_fmac_f32_e32 v26, v153, v31
	v_fmac_f32_e32 v34, v152, v39
	v_fmac_f32_e32 v42, v153, v47
	v_fmac_f32_e32 v50, v152, v55
	v_fmac_f32_e32 v58, v153, v63
	v_fmac_f32_e32 v2, v154, v8
	v_max_f32_e32 v17, 0, v17
	v_max_f32_e32 v25, 0, v25
	v_max_f32_e32 v33, 0, v33
	v_max_f32_e32 v41, 0, v41
	v_max_f32_e32 v49, 0, v49
	v_max_f32_e32 v57, 0, v57
	v_max_f32_e32 v65, 0, v65
	v_fmac_f32_e32 v10, v155, v16
	v_fmac_f32_e32 v18, v154, v24
	v_fmac_f32_e32 v26, v155, v32
	v_fmac_f32_e32 v34, v154, v40
	v_fmac_f32_e32 v42, v155, v48
	v_fmac_f32_e32 v50, v154, v56
	v_fmac_f32_e32 v58, v155, v64
	v_fmac_f32_e32 v2, v156, v9
	v_fmac_f32_e32 v10, v157, v17
	v_fmac_f32_e32 v18, v156, v25
	v_fmac_f32_e32 v26, v157, v33
	v_fmac_f32_e32 v34, v156, v41
	v_fmac_f32_e32 v42, v157, v49
	v_fmac_f32_e32 v50, v156, v57
	v_fmac_f32_e32 v58, v157, v65
	v_add_f32_e32 v2, 0, v2
	v_add_f32_e32 v3, 0, v10
	v_add_f32_e32 v4, 0, v18
	v_add_f32_e32 v5, 0, v26
	v_add_f32_e32 v6, 0, v34
	v_add_f32_e32 v7, 0, v42
	v_add_f32_e32 v8, 0, v50
	v_add_f32_e32 v9, 0, v58
	v_ashrrev_i32_e32 v10, 31, v2
	v_add_u32_e32 v124, 0x60, v148
	v_mov_b32_e32 v125, v149
	v_add_u32_e32 v148, 0x80, v148
	v_lshl_add_u64 v[122:123], v[128:129], 0, v[132:133]
	v_ashrrev_i32_e32 v11, 31, v3
	v_ashrrev_i32_e32 v12, 31, v4
	v_ashrrev_i32_e32 v13, 31, v5
	v_ashrrev_i32_e32 v14, 31, v6
	v_ashrrev_i32_e32 v15, 31, v7
	v_ashrrev_i32_e32 v16, 31, v8
	v_ashrrev_i32_e32 v17, 31, v9
	v_bitop3_b32 v2, v10, v2, s57 bitop3:0x36
	v_lshl_add_u64 v[118:119], v[130:131], 0, v[132:133]
	v_lshl_add_u64 v[120:121], v[134:135], 2, v[130:131]
	v_lshl_add_u64 v[132:133], v[136:137], 2, v[130:131]
	v_lshl_add_u64 v[124:125], v[124:125], 2, v[130:131]
	v_bitop3_b32 v3, v11, v3, s57 bitop3:0x36
	v_bitop3_b32 v4, v12, v4, s57 bitop3:0x36
	v_bitop3_b32 v5, v13, v5, s57 bitop3:0x36
	v_bitop3_b32 v6, v14, v6, s57 bitop3:0x36
	v_bitop3_b32 v7, v15, v7, s57 bitop3:0x36
	v_bitop3_b32 v8, v16, v8, s57 bitop3:0x36
	v_bitop3_b32 v9, v17, v9, s57 bitop3:0x36
	global_store_dword v[122:123], v2, off nt
	global_store_dword v[118:119], v3, off nt
	global_store_dword v[122:123], v4, off offset:128 nt
	global_store_dword v[120:121], v5, off nt
	global_store_dword v[122:123], v6, off offset:256 nt
	global_store_dword v[132:133], v7, off nt
	global_store_dword v[122:123], v8, off offset:384 nt
	global_store_dword v[124:125], v9, off nt
	s_cbranch_scc0 .LBB0_3056

.LBB0_3059:
	ds_read_b128 v[2:5], v22
	ds_read_b128 v[18:21], v22 offset:32
	s_add_i32 s9, s9, 1
	s_cmp_ge_i32 s9, s8
	s_waitcnt lgkmcnt(1)
	v_mfma_f32_32x32x16_bf16 v[2:17], v[74:77], v[2:5], 0
	s_waitcnt lgkmcnt(0)
	v_mfma_f32_32x32x16_bf16 v[2:17], v[70:73], v[18:21], v[2:17]
	ds_read_b128 v[24:27], v22 offset:64
	ds_read_b128 v[18:21], v22 offset:96
	v_add_u32_e32 v22, 0x1200, v22
	s_waitcnt lgkmcnt(1)
	v_mfma_f32_32x32x16_bf16 v[2:17], v[66:69], v[24:27], v[2:17]
	v_lshlrev_b64 v[24:25], 2, v[148:149]
	v_add_u32_e32 v148, 32, v148
	v_lshl_add_u64 v[26:27], v[128:129], 0, v[24:25]
	v_lshl_add_u64 v[24:25], v[130:131], 0, v[24:25]
	s_waitcnt lgkmcnt(0)
	v_mfma_f32_32x32x16_bf16 v[2:17], v[78:81], v[18:21], v[2:17]
	s_nop 11
	v_max_f32_e32 v2, 0, v2
	v_max_f32_e32 v10, 0, v10
	v_max_f32_e32 v3, 0, v3
	v_fma_f32 v2, v138, v2, 0
	v_max_f32_e32 v11, 0, v11
	v_max_f32_e32 v4, 0, v4
	v_fma_f32 v10, v139, v10, 0
	v_fmac_f32_e32 v2, v140, v3
	v_max_f32_e32 v12, 0, v12
	v_max_f32_e32 v5, 0, v5
	v_fmac_f32_e32 v10, v141, v11
	v_fmac_f32_e32 v2, v142, v4
	v_max_f32_e32 v13, 0, v13
	v_max_f32_e32 v6, 0, v6
	v_fmac_f32_e32 v10, v143, v12
	v_fmac_f32_e32 v2, v144, v5
	v_max_f32_e32 v14, 0, v14
	v_max_f32_e32 v7, 0, v7
	v_fmac_f32_e32 v10, v145, v13
	v_fmac_f32_e32 v2, v150, v6
	v_max_f32_e32 v15, 0, v15
	v_max_f32_e32 v8, 0, v8
	v_fmac_f32_e32 v10, v151, v14
	v_fmac_f32_e32 v2, v152, v7
	v_max_f32_e32 v16, 0, v16
	v_max_f32_e32 v9, 0, v9
	v_fmac_f32_e32 v10, v153, v15
	v_fmac_f32_e32 v2, v154, v8
	v_max_f32_e32 v17, 0, v17
	v_fmac_f32_e32 v10, v155, v16
	v_fmac_f32_e32 v2, v156, v9
	v_fmac_f32_e32 v10, v157, v17
	v_add_f32_e32 v2, 0, v2
	v_add_f32_e32 v3, 0, v10
	v_ashrrev_i32_e32 v4, 31, v2
	v_ashrrev_i32_e32 v5, 31, v3
	v_bitop3_b32 v2, v4, v2, s57 bitop3:0x36
	v_bitop3_b32 v3, v5, v3, s57 bitop3:0x36
	global_store_dword v[26:27], v2, off nt
	global_store_dword v[24:25], v3, off nt
	s_cbranch_scc0 .LBB0_3059
	s_branch .LBB0_3051
